# v168 with the four 8-phase GEMM main-loop heads aligned to 64 bytes (code placement)
# baseline (speedup 1.0000x reference)
.LBB0_307:
	s_ashr_i32 s21, s20, 31
	s_lshl_b64 s[22:23], s[20:21], 20
	s_add_u32 s22, s41, s22
	s_addc_u32 s23, s42, s23
	s_and_b64 s[24:25], s[38:39], exec
	s_cselect_b32 s21, s23, s27
	s_cselect_b32 s59, s22, s26
	s_lshl_b32 s24, s58, 20
	s_and_b32 s24, s24, 0xff00000
	s_add_u32 s24, s43, s24
	s_addc_u32 s25, s46, 0
	s_and_b64 s[30:31], s[38:39], exec
	s_cselect_b32 s60, s25, s29
	s_cselect_b32 s61, s24, s28
	s_add_u32 s26, s26, 0x80080
	s_addc_u32 s27, s27, 0
	s_add_u32 s62, s28, 0x100
	v_mov_b32_e32 v28, 0
	s_addc_u32 s63, s29, 0
	s_mov_b32 s64, -2
	v_mov_b32_e32 v29, v28
	v_mov_b32_e32 v30, v28
	v_mov_b32_e32 v31, v28
	v_mov_b32_e32 v32, v28
	v_mov_b32_e32 v33, v28
	v_mov_b32_e32 v34, v28
	v_mov_b32_e32 v35, v28
	v_mov_b32_e32 v36, v28
	v_mov_b32_e32 v37, v28
	v_mov_b32_e32 v38, v28
	v_mov_b32_e32 v39, v28
	v_mov_b32_e32 v40, v28
	v_mov_b32_e32 v41, v28
	v_mov_b32_e32 v42, v28
	v_mov_b32_e32 v43, v28
	v_mov_b32_e32 v52, v28
	v_mov_b32_e32 v53, v28
	v_mov_b32_e32 v54, v28
	v_mov_b32_e32 v55, v28
	v_mov_b32_e32 v56, v28
	v_mov_b32_e32 v57, v28
	v_mov_b32_e32 v58, v28
	v_mov_b32_e32 v59, v28
	v_mov_b32_e32 v68, v28
	v_mov_b32_e32 v69, v28
	v_mov_b32_e32 v70, v28
	v_mov_b32_e32 v71, v28
	v_mov_b32_e32 v72, v28
	v_mov_b32_e32 v73, v28
	v_mov_b32_e32 v74, v28
	v_mov_b32_e32 v75, v28
	v_mov_b32_e32 v44, v28
	v_mov_b32_e32 v45, v28
	v_mov_b32_e32 v46, v28
	v_mov_b32_e32 v47, v28
	v_mov_b32_e32 v48, v28
	v_mov_b32_e32 v49, v28
	v_mov_b32_e32 v50, v28
	v_mov_b32_e32 v51, v28
	v_mov_b32_e32 v60, v28
	v_mov_b32_e32 v61, v28
	v_mov_b32_e32 v62, v28
	v_mov_b32_e32 v63, v28
	v_mov_b32_e32 v64, v28
	v_mov_b32_e32 v65, v28
	v_mov_b32_e32 v66, v28
	v_mov_b32_e32 v67, v28
	v_mov_b32_e32 v76, v28
	v_mov_b32_e32 v77, v28
	v_mov_b32_e32 v78, v28
	v_mov_b32_e32 v79, v28
	v_mov_b32_e32 v80, v28
	v_mov_b32_e32 v81, v28
	v_mov_b32_e32 v82, v28
	v_mov_b32_e32 v83, v28
	v_mov_b32_e32 v84, v28
	v_mov_b32_e32 v85, v28
	v_mov_b32_e32 v86, v28
	v_mov_b32_e32 v87, v28
	v_mov_b32_e32 v88, v28
	v_mov_b32_e32 v89, v28
	v_mov_b32_e32 v90, v28
	v_mov_b32_e32 v91, v28
	v_mov_b32_e32 v92, v28
	v_mov_b32_e32 v93, v28
	v_mov_b32_e32 v94, v28
	v_mov_b32_e32 v95, v28
	v_mov_b32_e32 v96, v28
	v_mov_b32_e32 v97, v28
	v_mov_b32_e32 v98, v28
	v_mov_b32_e32 v99, v28
	v_mov_b32_e32 v100, v28
	v_mov_b32_e32 v101, v28
	v_mov_b32_e32 v102, v28
	v_mov_b32_e32 v103, v28
	v_mov_b32_e32 v104, v28
	v_mov_b32_e32 v105, v28
	v_mov_b32_e32 v106, v28
	v_mov_b32_e32 v107, v28
	v_mov_b32_e32 v116, v28
	v_mov_b32_e32 v117, v28
	v_mov_b32_e32 v118, v28
	v_mov_b32_e32 v119, v28
	v_mov_b32_e32 v120, v28
	v_mov_b32_e32 v121, v28
	v_mov_b32_e32 v122, v28
	v_mov_b32_e32 v123, v28
	v_mov_b32_e32 v132, v28
	v_mov_b32_e32 v133, v28
	v_mov_b32_e32 v134, v28
	v_mov_b32_e32 v135, v28
	v_mov_b32_e32 v136, v28
	v_mov_b32_e32 v137, v28
	v_mov_b32_e32 v138, v28
	v_mov_b32_e32 v139, v28
	v_mov_b32_e32 v108, v28
	v_mov_b32_e32 v109, v28
	v_mov_b32_e32 v110, v28
	v_mov_b32_e32 v111, v28
	v_mov_b32_e32 v112, v28
	v_mov_b32_e32 v113, v28
	v_mov_b32_e32 v114, v28
	v_mov_b32_e32 v115, v28
	v_mov_b32_e32 v124, v28
	v_mov_b32_e32 v125, v28
	v_mov_b32_e32 v126, v28
	v_mov_b32_e32 v127, v28
	v_mov_b32_e32 v128, v28
	v_mov_b32_e32 v129, v28
	v_mov_b32_e32 v130, v28
	v_mov_b32_e32 v131, v28
	v_mov_b32_e32 v140, v28
	v_mov_b32_e32 v141, v28
	v_mov_b32_e32 v142, v28
	v_mov_b32_e32 v143, v28
	v_mov_b32_e32 v144, v28
	v_mov_b32_e32 v145, v28
	v_mov_b32_e32 v146, v28
	v_mov_b32_e32 v147, v28
	v_mov_b32_e32 v148, v28
	v_mov_b32_e32 v149, v28
	v_mov_b32_e32 v150, v28
	v_mov_b32_e32 v151, v28
	v_mov_b32_e32 v152, v28
	v_mov_b32_e32 v153, v28
	v_mov_b32_e32 v154, v28
	v_mov_b32_e32 v155, v28
	.p2align	6

.LBB0_1333:
	s_add_i32 s9, s39, -2
	s_add_u32 s12, s12, 0x80080
	s_addc_u32 s13, s13, 0
	s_add_u32 s20, s16, 0x100
	v_mov_b32_e32 v28, 0
	s_addc_u32 s21, s17, 0
	s_mov_b32 s16, 0
	v_mov_b32_e32 v29, v28
	v_mov_b32_e32 v30, v28
	v_mov_b32_e32 v31, v28
	v_mov_b32_e32 v32, v28
	v_mov_b32_e32 v33, v28
	v_mov_b32_e32 v34, v28
	v_mov_b32_e32 v35, v28
	v_mov_b32_e32 v44, v28
	v_mov_b32_e32 v45, v28
	v_mov_b32_e32 v46, v28
	v_mov_b32_e32 v47, v28
	v_mov_b32_e32 v48, v28
	v_mov_b32_e32 v49, v28
	v_mov_b32_e32 v50, v28
	v_mov_b32_e32 v51, v28
	v_mov_b32_e32 v60, v28
	v_mov_b32_e32 v61, v28
	v_mov_b32_e32 v62, v28
	v_mov_b32_e32 v63, v28
	v_mov_b32_e32 v64, v28
	v_mov_b32_e32 v65, v28
	v_mov_b32_e32 v66, v28
	v_mov_b32_e32 v67, v28
	v_mov_b32_e32 v76, v28
	v_mov_b32_e32 v77, v28
	v_mov_b32_e32 v78, v28
	v_mov_b32_e32 v79, v28
	v_mov_b32_e32 v80, v28
	v_mov_b32_e32 v81, v28
	v_mov_b32_e32 v82, v28
	v_mov_b32_e32 v83, v28
	v_mov_b32_e32 v36, v28
	v_mov_b32_e32 v37, v28
	v_mov_b32_e32 v38, v28
	v_mov_b32_e32 v39, v28
	v_mov_b32_e32 v40, v28
	v_mov_b32_e32 v41, v28
	v_mov_b32_e32 v42, v28
	v_mov_b32_e32 v43, v28
	v_mov_b32_e32 v52, v28
	v_mov_b32_e32 v53, v28
	v_mov_b32_e32 v54, v28
	v_mov_b32_e32 v55, v28
	v_mov_b32_e32 v56, v28
	v_mov_b32_e32 v57, v28
	v_mov_b32_e32 v58, v28
	v_mov_b32_e32 v59, v28
	v_mov_b32_e32 v68, v28
	v_mov_b32_e32 v69, v28
	v_mov_b32_e32 v70, v28
	v_mov_b32_e32 v71, v28
	v_mov_b32_e32 v72, v28
	v_mov_b32_e32 v73, v28
	v_mov_b32_e32 v74, v28
	v_mov_b32_e32 v75, v28
	v_mov_b32_e32 v92, v28
	v_mov_b32_e32 v93, v28
	v_mov_b32_e32 v94, v28
	v_mov_b32_e32 v95, v28
	v_mov_b32_e32 v96, v28
	v_mov_b32_e32 v97, v28
	v_mov_b32_e32 v98, v28
	v_mov_b32_e32 v99, v28
	v_mov_b32_e32 v108, v28
	v_mov_b32_e32 v109, v28
	v_mov_b32_e32 v110, v28
	v_mov_b32_e32 v111, v28
	v_mov_b32_e32 v112, v28
	v_mov_b32_e32 v113, v28
	v_mov_b32_e32 v114, v28
	v_mov_b32_e32 v115, v28
	v_mov_b32_e32 v124, v28
	v_mov_b32_e32 v125, v28
	v_mov_b32_e32 v126, v28
	v_mov_b32_e32 v127, v28
	v_mov_b32_e32 v128, v28
	v_mov_b32_e32 v129, v28
	v_mov_b32_e32 v130, v28
	v_mov_b32_e32 v131, v28
	v_mov_b32_e32 v140, v28
	v_mov_b32_e32 v141, v28
	v_mov_b32_e32 v142, v28
	v_mov_b32_e32 v143, v28
	v_mov_b32_e32 v144, v28
	v_mov_b32_e32 v145, v28
	v_mov_b32_e32 v146, v28
	v_mov_b32_e32 v147, v28
	v_mov_b32_e32 v156, v28
	v_mov_b32_e32 v157, v28
	v_mov_b32_e32 v158, v28
	v_mov_b32_e32 v159, v28
	v_mov_b32_e32 v160, v28
	v_mov_b32_e32 v161, v28
	v_mov_b32_e32 v162, v28
	v_mov_b32_e32 v163, v28
	v_mov_b32_e32 v116, v28
	v_mov_b32_e32 v117, v28
	v_mov_b32_e32 v118, v28
	v_mov_b32_e32 v119, v28
	v_mov_b32_e32 v120, v28
	v_mov_b32_e32 v121, v28
	v_mov_b32_e32 v122, v28
	v_mov_b32_e32 v123, v28
	v_mov_b32_e32 v132, v28
	v_mov_b32_e32 v133, v28
	v_mov_b32_e32 v134, v28
	v_mov_b32_e32 v135, v28
	v_mov_b32_e32 v136, v28
	v_mov_b32_e32 v137, v28
	v_mov_b32_e32 v138, v28
	v_mov_b32_e32 v139, v28
	v_mov_b32_e32 v148, v28
	v_mov_b32_e32 v149, v28
	v_mov_b32_e32 v150, v28
	v_mov_b32_e32 v151, v28
	v_mov_b32_e32 v152, v28
	v_mov_b32_e32 v153, v28
	v_mov_b32_e32 v154, v28
	v_mov_b32_e32 v155, v28
	v_mov_b32_e32 v164, v28
	v_mov_b32_e32 v165, v28
	v_mov_b32_e32 v166, v28
	v_mov_b32_e32 v167, v28
	v_mov_b32_e32 v168, v28
	v_mov_b32_e32 v169, v28
	v_mov_b32_e32 v170, v28
	v_mov_b32_e32 v171, v28
	.p2align	6

.LBB0_1579:
	s_ashr_i32 s53, s52, 31
	s_lshl_b64 s[18:19], s[52:53], 20
	s_add_u32 s54, s24, s18
	s_addc_u32 s55, s25, s19
	s_and_b64 s[18:19], s[38:39], exec
	s_cselect_b32 s53, s55, s13
	s_cselect_b32 s64, s54, s12
	s_lshl_b32 s18, s63, 20
	s_and_b32 s18, s18, 0xff00000
	s_add_u32 s56, s26, s18
	s_addc_u32 s57, s27, 0
	s_and_b64 s[18:19], s[38:39], exec
	s_cselect_b32 s65, s57, s17
	s_cselect_b32 s66, s56, s16
	s_add_u32 s12, s12, 0x80080
	s_addc_u32 s13, s13, 0
	s_add_u32 s67, s16, 0x100
	v_mov_b32_e32 v28, 0
	s_addc_u32 s68, s17, 0
	s_mov_b32 s69, -2
	v_mov_b32_e32 v29, v28
	v_mov_b32_e32 v30, v28
	v_mov_b32_e32 v31, v28
	v_mov_b32_e32 v36, v28
	v_mov_b32_e32 v37, v28
	v_mov_b32_e32 v38, v28
	v_mov_b32_e32 v39, v28
	v_mov_b32_e32 v44, v28
	v_mov_b32_e32 v45, v28
	v_mov_b32_e32 v46, v28
	v_mov_b32_e32 v47, v28
	v_mov_b32_e32 v52, v28
	v_mov_b32_e32 v53, v28
	v_mov_b32_e32 v54, v28
	v_mov_b32_e32 v55, v28
	v_mov_b32_e32 v60, v28
	v_mov_b32_e32 v61, v28
	v_mov_b32_e32 v62, v28
	v_mov_b32_e32 v63, v28
	v_mov_b32_e32 v68, v28
	v_mov_b32_e32 v69, v28
	v_mov_b32_e32 v70, v28
	v_mov_b32_e32 v71, v28
	v_mov_b32_e32 v76, v28
	v_mov_b32_e32 v77, v28
	v_mov_b32_e32 v78, v28
	v_mov_b32_e32 v79, v28
	v_mov_b32_e32 v84, v28
	v_mov_b32_e32 v85, v28
	v_mov_b32_e32 v86, v28
	v_mov_b32_e32 v87, v28
	v_mov_b32_e32 v32, v28
	v_mov_b32_e32 v33, v28
	v_mov_b32_e32 v34, v28
	v_mov_b32_e32 v35, v28
	v_mov_b32_e32 v40, v28
	v_mov_b32_e32 v41, v28
	v_mov_b32_e32 v42, v28
	v_mov_b32_e32 v43, v28
	v_mov_b32_e32 v48, v28
	v_mov_b32_e32 v49, v28
	v_mov_b32_e32 v50, v28
	v_mov_b32_e32 v51, v28
	v_mov_b32_e32 v56, v28
	v_mov_b32_e32 v57, v28
	v_mov_b32_e32 v58, v28
	v_mov_b32_e32 v59, v28
	v_mov_b32_e32 v64, v28
	v_mov_b32_e32 v65, v28
	v_mov_b32_e32 v66, v28
	v_mov_b32_e32 v67, v28
	v_mov_b32_e32 v72, v28
	v_mov_b32_e32 v73, v28
	v_mov_b32_e32 v74, v28
	v_mov_b32_e32 v75, v28
	v_mov_b32_e32 v80, v28
	v_mov_b32_e32 v81, v28
	v_mov_b32_e32 v82, v28
	v_mov_b32_e32 v83, v28
	v_mov_b32_e32 v88, v28
	v_mov_b32_e32 v89, v28
	v_mov_b32_e32 v90, v28
	v_mov_b32_e32 v91, v28
	v_mov_b32_e32 v92, v28
	v_mov_b32_e32 v93, v28
	v_mov_b32_e32 v94, v28
	v_mov_b32_e32 v95, v28
	v_mov_b32_e32 v100, v28
	v_mov_b32_e32 v101, v28
	v_mov_b32_e32 v102, v28
	v_mov_b32_e32 v103, v28
	v_mov_b32_e32 v108, v28
	v_mov_b32_e32 v109, v28
	v_mov_b32_e32 v110, v28
	v_mov_b32_e32 v111, v28
	v_mov_b32_e32 v116, v28
	v_mov_b32_e32 v117, v28
	v_mov_b32_e32 v118, v28
	v_mov_b32_e32 v119, v28
	v_mov_b32_e32 v124, v28
	v_mov_b32_e32 v125, v28
	v_mov_b32_e32 v126, v28
	v_mov_b32_e32 v127, v28
	v_mov_b32_e32 v132, v28
	v_mov_b32_e32 v133, v28
	v_mov_b32_e32 v134, v28
	v_mov_b32_e32 v135, v28
	v_mov_b32_e32 v140, v28
	v_mov_b32_e32 v141, v28
	v_mov_b32_e32 v142, v28
	v_mov_b32_e32 v143, v28
	v_mov_b32_e32 v148, v28
	v_mov_b32_e32 v149, v28
	v_mov_b32_e32 v150, v28
	v_mov_b32_e32 v151, v28
	v_mov_b32_e32 v96, v28
	v_mov_b32_e32 v97, v28
	v_mov_b32_e32 v98, v28
	v_mov_b32_e32 v99, v28
	v_mov_b32_e32 v104, v28
	v_mov_b32_e32 v105, v28
	v_mov_b32_e32 v106, v28
	v_mov_b32_e32 v107, v28
	v_mov_b32_e32 v112, v28
	v_mov_b32_e32 v113, v28
	v_mov_b32_e32 v114, v28
	v_mov_b32_e32 v115, v28
	v_mov_b32_e32 v120, v28
	v_mov_b32_e32 v121, v28
	v_mov_b32_e32 v122, v28
	v_mov_b32_e32 v123, v28
	v_mov_b32_e32 v128, v28
	v_mov_b32_e32 v129, v28
	v_mov_b32_e32 v130, v28
	v_mov_b32_e32 v131, v28
	v_mov_b32_e32 v136, v28
	v_mov_b32_e32 v137, v28
	v_mov_b32_e32 v138, v28
	v_mov_b32_e32 v139, v28
	v_mov_b32_e32 v144, v28
	v_mov_b32_e32 v145, v28
	v_mov_b32_e32 v146, v28
	v_mov_b32_e32 v147, v28
	v_mov_b32_e32 v152, v28
	v_mov_b32_e32 v153, v28
	v_mov_b32_e32 v154, v28
	v_mov_b32_e32 v155, v28
	.p2align	6

.LBB0_1698:
	s_add_i32 s20, s70, -2
	s_add_u32 s21, s12, 0x100
	v_mov_b32_e32 v28, 0
	s_addc_u32 s71, s13, 0
	s_mov_b32 s16, 0
	v_mov_b32_e32 v29, v28
	v_mov_b32_e32 v30, v28
	v_mov_b32_e32 v31, v28
	v_mov_b32_e32 v32, v28
	v_mov_b32_e32 v33, v28
	v_mov_b32_e32 v34, v28
	v_mov_b32_e32 v35, v28
	v_mov_b32_e32 v44, v28
	v_mov_b32_e32 v45, v28
	v_mov_b32_e32 v46, v28
	v_mov_b32_e32 v47, v28
	v_mov_b32_e32 v48, v28
	v_mov_b32_e32 v49, v28
	v_mov_b32_e32 v50, v28
	v_mov_b32_e32 v51, v28
	v_mov_b32_e32 v76, v28
	v_mov_b32_e32 v77, v28
	v_mov_b32_e32 v78, v28
	v_mov_b32_e32 v79, v28
	v_mov_b32_e32 v80, v28
	v_mov_b32_e32 v81, v28
	v_mov_b32_e32 v82, v28
	v_mov_b32_e32 v83, v28
	v_mov_b32_e32 v92, v28
	v_mov_b32_e32 v93, v28
	v_mov_b32_e32 v94, v28
	v_mov_b32_e32 v95, v28
	v_mov_b32_e32 v96, v28
	v_mov_b32_e32 v97, v28
	v_mov_b32_e32 v98, v28
	v_mov_b32_e32 v99, v28
	v_mov_b32_e32 v36, v28
	v_mov_b32_e32 v37, v28
	v_mov_b32_e32 v38, v28
	v_mov_b32_e32 v39, v28
	v_mov_b32_e32 v40, v28
	v_mov_b32_e32 v41, v28
	v_mov_b32_e32 v42, v28
	v_mov_b32_e32 v43, v28
	v_mov_b32_e32 v52, v28
	v_mov_b32_e32 v53, v28
	v_mov_b32_e32 v54, v28
	v_mov_b32_e32 v55, v28
	v_mov_b32_e32 v56, v28
	v_mov_b32_e32 v57, v28
	v_mov_b32_e32 v58, v28
	v_mov_b32_e32 v59, v28
	v_mov_b32_e32 v84, v28
	v_mov_b32_e32 v85, v28
	v_mov_b32_e32 v86, v28
	v_mov_b32_e32 v87, v28
	v_mov_b32_e32 v88, v28
	v_mov_b32_e32 v89, v28
	v_mov_b32_e32 v90, v28
	v_mov_b32_e32 v91, v28
	v_mov_b32_e32 v100, v28
	v_mov_b32_e32 v101, v28
	v_mov_b32_e32 v102, v28
	v_mov_b32_e32 v103, v28
	v_mov_b32_e32 v104, v28
	v_mov_b32_e32 v105, v28
	v_mov_b32_e32 v106, v28
	v_mov_b32_e32 v107, v28
	v_mov_b32_e32 v108, v28
	v_mov_b32_e32 v109, v28
	v_mov_b32_e32 v110, v28
	v_mov_b32_e32 v111, v28
	v_mov_b32_e32 v112, v28
	v_mov_b32_e32 v113, v28
	v_mov_b32_e32 v114, v28
	v_mov_b32_e32 v115, v28
	v_mov_b32_e32 v124, v28
	v_mov_b32_e32 v125, v28
	v_mov_b32_e32 v126, v28
	v_mov_b32_e32 v127, v28
	v_mov_b32_e32 v128, v28
	v_mov_b32_e32 v129, v28
	v_mov_b32_e32 v130, v28
	v_mov_b32_e32 v131, v28
	v_mov_b32_e32 v140, v28
	v_mov_b32_e32 v141, v28
	v_mov_b32_e32 v142, v28
	v_mov_b32_e32 v143, v28
	v_mov_b32_e32 v144, v28
	v_mov_b32_e32 v145, v28
	v_mov_b32_e32 v146, v28
	v_mov_b32_e32 v147, v28
	v_mov_b32_e32 v156, v28
	v_mov_b32_e32 v157, v28
	v_mov_b32_e32 v158, v28
	v_mov_b32_e32 v159, v28
	v_mov_b32_e32 v160, v28
	v_mov_b32_e32 v161, v28
	v_mov_b32_e32 v162, v28
	v_mov_b32_e32 v163, v28
	v_mov_b32_e32 v116, v28
	v_mov_b32_e32 v117, v28
	v_mov_b32_e32 v118, v28
	v_mov_b32_e32 v119, v28
	v_mov_b32_e32 v120, v28
	v_mov_b32_e32 v121, v28
	v_mov_b32_e32 v122, v28
	v_mov_b32_e32 v123, v28
	v_mov_b32_e32 v132, v28
	v_mov_b32_e32 v133, v28
	v_mov_b32_e32 v134, v28
	v_mov_b32_e32 v135, v28
	v_mov_b32_e32 v136, v28
	v_mov_b32_e32 v137, v28
	v_mov_b32_e32 v138, v28
	v_mov_b32_e32 v139, v28
	v_mov_b32_e32 v148, v28
	v_mov_b32_e32 v149, v28
	v_mov_b32_e32 v150, v28
	v_mov_b32_e32 v151, v28
	v_mov_b32_e32 v152, v28
	v_mov_b32_e32 v153, v28
	v_mov_b32_e32 v154, v28
	v_mov_b32_e32 v155, v28
	v_mov_b32_e32 v164, v28
	v_mov_b32_e32 v165, v28
	v_mov_b32_e32 v166, v28
	v_mov_b32_e32 v167, v28
	v_mov_b32_e32 v168, v28
	v_mov_b32_e32 v169, v28
	v_mov_b32_e32 v170, v28
	v_mov_b32_e32 v171, v28
	.p2align	6
